# v57 + removed 128 redundant canonicalising v_max_f32 v,v,v from the MLP-up (relu^2) GEMM epilogue; vcc-cndmask spacing kept at 2
# speedup vs baseline: 1.0049x; 1.0049x over previous
.LBB0_1120:
	v_add_u32_e32 v144, s35, v140
	s_movk_i32 s9, 0x4000
	v_max_f32_e32 v126, 0, v126
	v_max_f32_e32 v127, 0, v127
	v_max_f32_e32 v124, 0, v124
	v_max_f32_e32 v125, 0, v125
	v_max_f32_e32 v120, 0, v120
	v_max_f32_e32 v121, 0, v121
	v_add_u32_e32 v145, 0xffffc000, v144
	v_ashrrev_i32_e32 v146, 31, v144
	v_cmp_gt_i32_e32 vcc, s9, v144
	v_pk_mul_f32 v[126:127], v[126:127], v[126:127]
	v_pk_mul_f32 v[124:125], v[124:125], v[124:125]
	v_max_f32_e32 v122, 0, v122
	v_max_f32_e32 v123, 0, v123
	v_pk_mul_f32 v[120:121], v[120:121], v[120:121]
	v_max_f32_e32 v118, 0, v118
	v_max_f32_e32 v119, 0, v119
	v_max_f32_e32 v116, 0, v116
	v_max_f32_e32 v117, 0, v117
	v_max_f32_e32 v112, 0, v112
	v_max_f32_e32 v113, 0, v113
	v_cndmask_b32_e32 v151, 0, v146, vcc
	v_cndmask_b32_e32 v150, v145, v144, vcc
	v_mov_b32_e32 v145, s83
	v_mov_b32_e32 v146, s89
	v_mov_b32_e32 v147, s82
	v_mov_b32_e32 v148, s88
	v_cvt_pk_bf16_f32 v127, v126, v127
	v_cvt_pk_bf16_f32 v126, v124, v125
	v_pk_mul_f32 v[122:123], v[122:123], v[122:123]
	v_cvt_pk_bf16_f32 v124, v120, v121
	v_add_u32_e32 v120, 16, v144
	v_pk_mul_f32 v[118:119], v[118:119], v[118:119]
	v_pk_mul_f32 v[116:117], v[116:117], v[116:117]
	v_max_f32_e32 v114, 0, v114
	v_max_f32_e32 v115, 0, v115
	v_pk_mul_f32 v[112:113], v[112:113], v[112:113]
	v_max_f32_e32 v110, 0, v110
	v_max_f32_e32 v111, 0, v111
	v_max_f32_e32 v108, 0, v108
	v_max_f32_e32 v109, 0, v109
	v_max_f32_e32 v104, 0, v104
	v_max_f32_e32 v105, 0, v105
	v_cndmask_b32_e32 v153, v145, v146, vcc
	v_cndmask_b32_e32 v152, v147, v148, vcc
	v_cvt_pk_bf16_f32 v125, v122, v123
	v_add_u32_e32 v122, 0xffffc010, v144
	v_ashrrev_i32_e32 v121, 31, v120
	v_cmp_gt_i32_e32 vcc, s9, v120
	v_cvt_pk_bf16_f32 v119, v118, v119
	v_cvt_pk_bf16_f32 v118, v116, v117
	v_pk_mul_f32 v[114:115], v[114:115], v[114:115]
	v_cvt_pk_bf16_f32 v116, v112, v113
	v_add_u32_e32 v112, 32, v144
	v_pk_mul_f32 v[110:111], v[110:111], v[110:111]
	v_pk_mul_f32 v[108:109], v[108:109], v[108:109]
	v_max_f32_e32 v106, 0, v106
	v_max_f32_e32 v107, 0, v107
	v_pk_mul_f32 v[104:105], v[104:105], v[104:105]
	v_max_f32_e32 v70, 0, v70
	v_max_f32_e32 v71, 0, v71
	v_max_f32_e32 v68, 0, v68
	v_max_f32_e32 v69, 0, v69
	v_max_f32_e32 v64, 0, v64
	v_max_f32_e32 v65, 0, v65
	v_cndmask_b32_e32 v121, 0, v121, vcc
	v_cndmask_b32_e32 v120, v122, v120, vcc
	v_cndmask_b32_e32 v123, v145, v146, vcc
	v_cndmask_b32_e32 v122, v147, v148, vcc
	v_cvt_pk_bf16_f32 v117, v114, v115
	v_add_u32_e32 v114, 0xffffc020, v144
	v_ashrrev_i32_e32 v113, 31, v112
	v_cmp_gt_i32_e32 vcc, s9, v112
	v_cvt_pk_bf16_f32 v111, v110, v111
	v_cvt_pk_bf16_f32 v110, v108, v109
	v_pk_mul_f32 v[106:107], v[106:107], v[106:107]
	v_cvt_pk_bf16_f32 v108, v104, v105
	v_add_u32_e32 v104, 48, v144
	v_pk_mul_f32 v[70:71], v[70:71], v[70:71]
	v_pk_mul_f32 v[68:69], v[68:69], v[68:69]
	v_max_f32_e32 v66, 0, v66
	v_max_f32_e32 v67, 0, v67
	v_pk_mul_f32 v[64:65], v[64:65], v[64:65]
	v_max_f32_e32 v62, 0, v62
	v_max_f32_e32 v63, 0, v63
	v_max_f32_e32 v60, 0, v60
	v_max_f32_e32 v61, 0, v61
	v_max_f32_e32 v56, 0, v56
	v_max_f32_e32 v57, 0, v57
	v_cndmask_b32_e32 v113, 0, v113, vcc
	v_cndmask_b32_e32 v112, v114, v112, vcc
	v_cndmask_b32_e32 v115, v145, v146, vcc
	v_cndmask_b32_e32 v114, v147, v148, vcc
	v_cvt_pk_bf16_f32 v109, v106, v107
	v_add_u32_e32 v106, 0xffffc030, v144
	v_ashrrev_i32_e32 v105, 31, v104
	v_cmp_gt_i32_e32 vcc, s9, v104
	v_cvt_pk_bf16_f32 v71, v70, v71
	v_cvt_pk_bf16_f32 v70, v68, v69
	v_pk_mul_f32 v[66:67], v[66:67], v[66:67]
	v_cvt_pk_bf16_f32 v68, v64, v65
	v_add_u32_e32 v64, 0x80, v144
	v_pk_mul_f32 v[62:63], v[62:63], v[62:63]
	v_pk_mul_f32 v[60:61], v[60:61], v[60:61]
	v_max_f32_e32 v58, 0, v58
	v_max_f32_e32 v59, 0, v59
	v_pk_mul_f32 v[56:57], v[56:57], v[56:57]
	v_max_f32_e32 v54, 0, v54
	v_max_f32_e32 v55, 0, v55
	v_max_f32_e32 v52, 0, v52
	v_max_f32_e32 v53, 0, v53
	v_max_f32_e32 v48, 0, v48
	v_max_f32_e32 v49, 0, v49
	v_cndmask_b32_e32 v105, 0, v105, vcc
	v_cndmask_b32_e32 v104, v106, v104, vcc
	v_cndmask_b32_e32 v107, v145, v146, vcc
	v_cndmask_b32_e32 v106, v147, v148, vcc
	v_cvt_pk_bf16_f32 v69, v66, v67
	v_add_u32_e32 v66, 0xffffc080, v144
	v_ashrrev_i32_e32 v65, 31, v64
	v_cmp_gt_i32_e32 vcc, s9, v64
	v_cvt_pk_bf16_f32 v63, v62, v63
	v_cvt_pk_bf16_f32 v62, v60, v61
	v_pk_mul_f32 v[58:59], v[58:59], v[58:59]
	v_cvt_pk_bf16_f32 v60, v56, v57
	v_add_u32_e32 v56, 0x90, v144
	v_pk_mul_f32 v[54:55], v[54:55], v[54:55]
	v_pk_mul_f32 v[52:53], v[52:53], v[52:53]
	v_max_f32_e32 v50, 0, v50
	v_max_f32_e32 v51, 0, v51
	v_pk_mul_f32 v[48:49], v[48:49], v[48:49]
	v_max_f32_e32 v46, 0, v46
	v_max_f32_e32 v47, 0, v47
	v_max_f32_e32 v44, 0, v44
	v_max_f32_e32 v45, 0, v45
	v_max_f32_e32 v40, 0, v40
	v_max_f32_e32 v41, 0, v41
	v_cndmask_b32_e32 v65, 0, v65, vcc
	v_cndmask_b32_e32 v64, v66, v64, vcc
	v_cndmask_b32_e32 v67, v145, v146, vcc
	v_cndmask_b32_e32 v66, v147, v148, vcc
	v_cvt_pk_bf16_f32 v61, v58, v59
	v_add_u32_e32 v58, 0xffffc090, v144
	v_ashrrev_i32_e32 v57, 31, v56
	v_cmp_gt_i32_e32 vcc, s9, v56
	v_cvt_pk_bf16_f32 v55, v54, v55
	v_cvt_pk_bf16_f32 v54, v52, v53
	v_pk_mul_f32 v[50:51], v[50:51], v[50:51]
	v_cvt_pk_bf16_f32 v52, v48, v49
	v_add_u32_e32 v48, 0xa0, v144
	v_pk_mul_f32 v[46:47], v[46:47], v[46:47]
	v_pk_mul_f32 v[44:45], v[44:45], v[44:45]
	v_max_f32_e32 v42, 0, v42
	v_max_f32_e32 v43, 0, v43
	v_pk_mul_f32 v[40:41], v[40:41], v[40:41]
	v_cndmask_b32_e32 v57, 0, v57, vcc
	v_cndmask_b32_e32 v56, v58, v56, vcc
	v_cndmask_b32_e32 v59, v145, v146, vcc
	v_cndmask_b32_e32 v58, v147, v148, vcc
	v_cvt_pk_bf16_f32 v53, v50, v51
	v_add_u32_e32 v50, 0xffffc0a0, v144
	v_ashrrev_i32_e32 v49, 31, v48
	v_cmp_gt_i32_e32 vcc, s9, v48
	v_cvt_pk_bf16_f32 v47, v46, v47
	v_cvt_pk_bf16_f32 v46, v44, v45
	v_pk_mul_f32 v[42:43], v[42:43], v[42:43]
	v_cvt_pk_bf16_f32 v44, v40, v41
	v_add_u32_e32 v40, 0xb0, v144
	v_cndmask_b32_e32 v49, 0, v49, vcc
	v_cndmask_b32_e32 v48, v50, v48, vcc
	v_cndmask_b32_e32 v51, v145, v146, vcc
	v_cndmask_b32_e32 v50, v147, v148, vcc
	v_cvt_pk_bf16_f32 v45, v42, v43
	v_add_u32_e32 v42, 0xffffc0b0, v144
	v_ashrrev_i32_e32 v41, 31, v40
	v_cmp_gt_i32_e32 vcc, s9, v40
	v_add_u32_e32 v138, s16, v142
	v_ashrrev_i32_e32 v139, 31, v138
	v_cndmask_b32_e32 v41, 0, v41, vcc
	v_cndmask_b32_e32 v40, v42, v40, vcc
	v_lshlrev_b64 v[150:151], 13, v[150:151]
	v_lshlrev_b64 v[120:121], 13, v[120:121]
	v_lshlrev_b64 v[112:113], 13, v[112:113]
	v_lshlrev_b64 v[104:105], 13, v[104:105]
	v_max_f32_e32 v102, 0, v102
	v_max_f32_e32 v103, 0, v103
	v_max_f32_e32 v100, 0, v100
	v_max_f32_e32 v101, 0, v101
	v_max_f32_e32 v98, 0, v98
	v_max_f32_e32 v99, 0, v99
	v_max_f32_e32 v96, 0, v96
	v_max_f32_e32 v97, 0, v97
	v_max_f32_e32 v94, 0, v94
	v_max_f32_e32 v95, 0, v95
	v_max_f32_e32 v92, 0, v92
	v_max_f32_e32 v93, 0, v93
	v_max_f32_e32 v90, 0, v90
	v_max_f32_e32 v91, 0, v91
	v_max_f32_e32 v88, 0, v88
	v_max_f32_e32 v89, 0, v89
	v_max_f32_e32 v86, 0, v86
	v_max_f32_e32 v87, 0, v87
	v_max_f32_e32 v84, 0, v84
	v_max_f32_e32 v85, 0, v85
	v_max_f32_e32 v82, 0, v82
	v_max_f32_e32 v83, 0, v83
	v_max_f32_e32 v80, 0, v80
	v_max_f32_e32 v81, 0, v81
	v_max_f32_e32 v78, 0, v78
	v_max_f32_e32 v79, 0, v79
	v_max_f32_e32 v76, 0, v76
	v_max_f32_e32 v77, 0, v77
	v_max_f32_e32 v74, 0, v74
	v_max_f32_e32 v75, 0, v75
	v_max_f32_e32 v72, 0, v72
	v_max_f32_e32 v73, 0, v73
	v_lshlrev_b64 v[64:65], 13, v[64:65]
	v_lshlrev_b64 v[56:57], 13, v[56:57]
	v_lshlrev_b64 v[48:49], 13, v[48:49]
	v_cndmask_b32_e32 v43, v145, v146, vcc
	v_cndmask_b32_e32 v42, v147, v148, vcc
	v_lshlrev_b64 v[40:41], 13, v[40:41]
	v_max_f32_e32 v38, 0, v38
	v_max_f32_e32 v39, 0, v39
	v_max_f32_e32 v36, 0, v36
	v_max_f32_e32 v37, 0, v37
	v_max_f32_e32 v34, 0, v34
	v_max_f32_e32 v35, 0, v35
	v_max_f32_e32 v32, 0, v32
	v_max_f32_e32 v33, 0, v33
	v_max_f32_e32 v30, 0, v30
	v_max_f32_e32 v31, 0, v31
	v_max_f32_e32 v28, 0, v28
	v_max_f32_e32 v29, 0, v29
	v_max_f32_e32 v26, 0, v26
	v_max_f32_e32 v27, 0, v27
	v_max_f32_e32 v24, 0, v24
	v_max_f32_e32 v25, 0, v25
	v_max_f32_e32 v22, 0, v22
	v_max_f32_e32 v23, 0, v23
	v_max_f32_e32 v20, 0, v20
	v_max_f32_e32 v21, 0, v21
	v_max_f32_e32 v18, 0, v18
	v_max_f32_e32 v19, 0, v19
	v_max_f32_e32 v16, 0, v16
	v_max_f32_e32 v17, 0, v17
	v_max_f32_e32 v14, 0, v14
	v_max_f32_e32 v15, 0, v15
	v_max_f32_e32 v12, 0, v12
	v_max_f32_e32 v13, 0, v13
	v_max_f32_e32 v10, 0, v10
	v_max_f32_e32 v11, 0, v11
	v_max_f32_e32 v8, 0, v8
	v_max_f32_e32 v9, 0, v9
	v_max_f32_e32 v6, 0, v6
	v_max_f32_e32 v7, 0, v7
	v_max_f32_e32 v4, 0, v4
	v_max_f32_e32 v5, 0, v5
	v_max_f32_e32 v2, 0, v2
	v_max_f32_e32 v3, 0, v3
	v_max_f32_e32 v0, 0, v0
	v_max_f32_e32 v1, 0, v1
	v_lshl_add_u64 v[150:151], v[152:153], 0, v[150:151]
	v_lshlrev_b64 v[138:139], 1, v[138:139]
	v_lshl_add_u64 v[120:121], v[122:123], 0, v[120:121]
	v_lshl_add_u64 v[112:113], v[114:115], 0, v[112:113]
	v_lshl_add_u64 v[104:105], v[106:107], 0, v[104:105]
	v_pk_mul_f32 v[102:103], v[102:103], v[102:103]
	v_pk_mul_f32 v[100:101], v[100:101], v[100:101]
	v_pk_mul_f32 v[98:99], v[98:99], v[98:99]
	v_pk_mul_f32 v[96:97], v[96:97], v[96:97]
	v_pk_mul_f32 v[94:95], v[94:95], v[94:95]
	v_pk_mul_f32 v[92:93], v[92:93], v[92:93]
	v_pk_mul_f32 v[90:91], v[90:91], v[90:91]
	v_pk_mul_f32 v[88:89], v[88:89], v[88:89]
	v_pk_mul_f32 v[86:87], v[86:87], v[86:87]
	v_pk_mul_f32 v[84:85], v[84:85], v[84:85]
	v_pk_mul_f32 v[82:83], v[82:83], v[82:83]
	v_pk_mul_f32 v[80:81], v[80:81], v[80:81]
	v_pk_mul_f32 v[78:79], v[78:79], v[78:79]
	v_pk_mul_f32 v[76:77], v[76:77], v[76:77]
	v_pk_mul_f32 v[74:75], v[74:75], v[74:75]
	v_pk_mul_f32 v[72:73], v[72:73], v[72:73]
	v_lshl_add_u64 v[64:65], v[66:67], 0, v[64:65]
	v_lshl_add_u64 v[56:57], v[58:59], 0, v[56:57]
	v_lshl_add_u64 v[48:49], v[50:51], 0, v[48:49]
	v_lshl_add_u64 v[40:41], v[42:43], 0, v[40:41]
	v_pk_mul_f32 v[38:39], v[38:39], v[38:39]
	v_pk_mul_f32 v[36:37], v[36:37], v[36:37]
	v_pk_mul_f32 v[34:35], v[34:35], v[34:35]
	v_pk_mul_f32 v[32:33], v[32:33], v[32:33]
	v_pk_mul_f32 v[30:31], v[30:31], v[30:31]
	v_pk_mul_f32 v[28:29], v[28:29], v[28:29]
	v_pk_mul_f32 v[26:27], v[26:27], v[26:27]
	v_pk_mul_f32 v[24:25], v[24:25], v[24:25]
	v_pk_mul_f32 v[22:23], v[22:23], v[22:23]
	v_pk_mul_f32 v[20:21], v[20:21], v[20:21]
	v_pk_mul_f32 v[18:19], v[18:19], v[18:19]
	v_pk_mul_f32 v[16:17], v[16:17], v[16:17]
	v_pk_mul_f32 v[14:15], v[14:15], v[14:15]
	v_pk_mul_f32 v[12:13], v[12:13], v[12:13]
	v_pk_mul_f32 v[10:11], v[10:11], v[10:11]
	v_pk_mul_f32 v[8:9], v[8:9], v[8:9]
	v_pk_mul_f32 v[6:7], v[6:7], v[6:7]
	v_pk_mul_f32 v[4:5], v[4:5], v[4:5]
	v_pk_mul_f32 v[2:3], v[2:3], v[2:3]
	v_pk_mul_f32 v[0:1], v[0:1], v[0:1]
	v_lshl_add_u64 v[150:151], v[150:151], 0, v[138:139]
	v_lshl_add_u64 v[120:121], v[120:121], 0, v[138:139]
	v_lshl_add_u64 v[112:113], v[112:113], 0, v[138:139]
	v_lshl_add_u64 v[104:105], v[104:105], 0, v[138:139]
	v_cvt_pk_bf16_f32 v103, v102, v103
	v_cvt_pk_bf16_f32 v102, v100, v101
	v_cvt_pk_bf16_f32 v101, v98, v99
	v_cvt_pk_bf16_f32 v100, v96, v97
	v_cvt_pk_bf16_f32 v95, v94, v95
	v_cvt_pk_bf16_f32 v94, v92, v93
	v_cvt_pk_bf16_f32 v93, v90, v91
	v_cvt_pk_bf16_f32 v92, v88, v89
	v_cvt_pk_bf16_f32 v87, v86, v87
	v_cvt_pk_bf16_f32 v86, v84, v85
	v_cvt_pk_bf16_f32 v85, v82, v83
	v_cvt_pk_bf16_f32 v84, v80, v81
	v_cvt_pk_bf16_f32 v79, v78, v79
	v_cvt_pk_bf16_f32 v78, v76, v77
	v_cvt_pk_bf16_f32 v77, v74, v75
	v_cvt_pk_bf16_f32 v76, v72, v73
	v_lshl_add_u64 v[64:65], v[64:65], 0, v[138:139]
	v_lshl_add_u64 v[56:57], v[56:57], 0, v[138:139]
	v_lshl_add_u64 v[48:49], v[48:49], 0, v[138:139]
	v_lshl_add_u64 v[40:41], v[40:41], 0, v[138:139]
	v_cvt_pk_bf16_f32 v39, v38, v39
	v_cvt_pk_bf16_f32 v38, v36, v37
	v_cvt_pk_bf16_f32 v37, v34, v35
	v_cvt_pk_bf16_f32 v36, v32, v33
	v_cvt_pk_bf16_f32 v31, v30, v31
	v_cvt_pk_bf16_f32 v30, v28, v29
	v_cvt_pk_bf16_f32 v29, v26, v27
	v_cvt_pk_bf16_f32 v28, v24, v25
	v_cvt_pk_bf16_f32 v23, v22, v23
	v_cvt_pk_bf16_f32 v22, v20, v21
	v_cvt_pk_bf16_f32 v21, v18, v19
	v_cvt_pk_bf16_f32 v20, v16, v17
	v_cvt_pk_bf16_f32 v15, v14, v15
	v_cvt_pk_bf16_f32 v14, v12, v13
	v_cvt_pk_bf16_f32 v13, v10, v11
	v_cvt_pk_bf16_f32 v12, v8, v9
	v_cvt_pk_bf16_f32 v7, v6, v7
	v_cvt_pk_bf16_f32 v6, v4, v5
	v_cvt_pk_bf16_f32 v5, v2, v3
	v_cvt_pk_bf16_f32 v4, v0, v1
	s_andn2_b64 vcc, exec, s[6:7]
	s_mov_b64 s[6:7], -1
	global_store_dwordx4 v[150:151], v[124:127], off
	global_store_dwordx4 v[120:121], v[116:119], off
	global_store_dwordx4 v[112:113], v[108:111], off
	global_store_dwordx4 v[104:105], v[100:103], off
	global_store_dwordx4 v[150:151], v[92:95], off offset:256
	global_store_dwordx4 v[120:121], v[84:87], off offset:256
	global_store_dwordx4 v[112:113], v[76:79], off offset:256
	global_store_dwordx4 v[104:105], v[68:71], off offset:256
	global_store_dwordx4 v[64:65], v[60:63], off
	global_store_dwordx4 v[56:57], v[52:55], off
	global_store_dwordx4 v[48:49], v[44:47], off
	global_store_dwordx4 v[40:41], v[36:39], off
	global_store_dwordx4 v[64:65], v[28:31], off offset:256
	global_store_dwordx4 v[56:57], v[20:23], off offset:256
	global_store_dwordx4 v[48:49], v[12:15], off offset:256
	global_store_dwordx4 v[40:41], v[4:7], off offset:256
	s_cbranch_vccnz .LBB0_1113
	s_andn2_b64 vcc, exec, s[0:1]
	s_cbranch_vccnz .LBB0_1112
	s_barrier
	s_branch .LBB0_1112
